# in-proj GEMM: 6 full rounds in the GEMM phase; the 64 tail tiles (last column tile) run on workgroups 0-63 at the start of the mixer phase, flagged complete before spatial gating
# speedup vs baseline: 1.0113x; 1.0037x over previous
; #define LAS __attribute__((address_space(3)))
; __device__ __forceinline__ unsigned xb_add(unsigned* p, unsigned v) { return __hip_atomic_fetch_add(p, v, __ATOMIC_RELAXED, __HIP_MEMORY_SCOPE_AGENT); }
; __device__ __forceinline__ unsigned xb_xcc_id() { return (unsigned)__builtin_amdgcn_s_getreg((3 << 11) | 20) & 0xFu; }
; __device__ __forceinline__ XcdBarrier xcd_barrier_post(unsigned* bar, volatile LAS unsigned* st) {
;     XcdBarrier b; b.bar = bar; b.x = xb_xcc_id(); b.st = st;
;     if (threadIdx.x == 0) (void)xb_add(&bar[XB_XCNT(b.x)], 1u);
;     return b;
; __global__ void __launch_bounds__(NTHR, 2) fwd(Args args) {
;     extern __shared__ __attribute__((aligned(16))) unsigned char lds_raw[];
;     LAS unsigned char* lds = (LAS unsigned char*)lds_raw;
;     volatile LAS int* MISC = (volatile LAS int*)(lds + MISC_OFF);
;     const int G = gridDim.x, NGW = G * NWAVES;
;     ...
;     const int lo = args.ph_lo, hi = args.ph_hi;
;     if (threadIdx.x < 64) MISC[threadIdx.x] = 0;
;     __syncthreads();
;     XcdBarrier bar = xcd_barrier_post(ctl + CW_BAR, (volatile LAS unsigned*)(MISC + 8));
_Z3fwd4Args:
	s_mov_b32 s98, 0
	s_mov_b32 s99, 0
	s_load_dwordx2 s[58:59], s[0:1], 0xb0
	s_load_dword s3, s[0:1], 0xb8
	s_add_u32 s4, s0, 0xb8
	s_addc_u32 s5, s1, 0
	v_and_b32_e32 v232, 0x3ff, v0
	v_writelane_b32 v254, s4, 0
	v_cmp_gt_u32_e32 vcc, 64, v232
	s_nop 0
	v_writelane_b32 v254, s5, 1
	s_and_saveexec_b64 s[4:5], vcc
	v_lshl_add_u32 v1, v232, 2, 0
	v_add_u32_e32 v1, 0x22000, v1
	v_mov_b32_e32 v2, 0
	ds_write_b32 v1, v2
	s_or_b64 exec, exec, s[4:5]
	s_mov_b32 s4, 21
	s_waitcnt lgkmcnt(0)
	s_barrier
	s_ashr_i32 s5, s4, 31
	s_lshl_b64 s[4:5], s[4:5], 3
	s_add_u32 s4, s0, s4
	s_addc_u32 s5, s1, s5
	s_load_dwordx2 s[8:9], s[4:5], 0x0
	s_getreg_b32 s4, hwreg(HW_REG_XCC_ID, 0, 4)
	v_cmp_eq_u32_e64 s[74:75], 0, v232
	s_waitcnt lgkmcnt(0)
	s_add_u32 s10, s8, 0x8000
	s_addc_u32 s11, s9, 0
	s_and_b32 s52, s4, 15
	s_and_saveexec_b64 s[4:5], s[74:75]
	s_cbranch_execz .LBB0_5
	s_mov_b64 s[6:7], exec
	v_mbcnt_lo_u32_b32 v1, s6, 0
	v_mbcnt_hi_u32_b32 v1, s7, v1
	v_cmp_eq_u32_e32 vcc, 0, v1
	s_and_b64 s[12:13], exec, vcc
	s_mov_b64 exec, s[12:13]
	s_cbranch_execz .LBB0_5
	s_lshl_b32 s12, s52, 8
	s_bcnt1_i32_b64 s6, s[6:7]
	v_mov_b32_e32 v1, s12
	v_mov_b32_e32 v2, s6
	global_atomic_add v1, v2, s[10:11] offset:1024

;     __device__ __forceinline__ bool next(int i, Unit& u) const { if (i) return false; u.pm = pm; u.pn = pn; return true; }
; #define PIN_TID() int tid = threadIdx.x; asm volatile("" : "+v"(tid)); const int lane = tid & 63, wid = __builtin_amdgcn_readfirstlane(tid >> 6), gw = blockIdx.x * NWAVES + wid; (void)lane; (void)gw
;     __host__ __device__ bool next(int i, Unit& u) const {
;         const long L = (long)i * G + c; if (L >= nwg) return false;
;         int wgid = (int)L; { const int q = nwg / NXCD, r = nwg % NXCD, xcd = wgid % NXCD, off = wgid / NXCD; wgid = (xcd < r ? xcd * (q + 1) : r * (q + 1) + (xcd - r) * q) + off; }
;         const int nig = WGM * nN, gid = wgid / nig, fm = gid * WGM, gsz = (nM - fm) < WGM ? (nM - fm) : WGM;
;         u.pm = fm + ((wgid % nig) % gsz); u.pn = (wgid % nig) / gsz; return true;
;     }
; __global__ void __launch_bounds__(NTHR, 2) fwd(Args args) {
;     ...
;     for (int l = 0; l < DEPTH; ++l) {
;     ...
;         if (XEN(1) && IN_PH()) for (int rep = 0; rep < XREP(1); ++rep) { PIN_TID();
;             pg8::Gemm g{XN, WIN + (size_t)l * INW * DM, M, INW, DM}; pg8::StaticOrder S; S.init(M, INW - 256 * XTAIL, G, (int)blockIdx.x);
;             pg8::EpiProj E{PROJ, INW, RS};
;             pg8::gemm_phase<pg8::EpiProj, pg8::StaticOrder, PG8ALIGN, PG8SP2>(lds, g, S, E);
.LBB0_124:
	s_cmpk_lt_i32 s2, 0x640
	s_cselect_b64 s[4:5], -1, 0
	v_writelane_b32 v254, s4, 2
	s_ashr_i32 s33, s2, 31
	s_ashr_i32 s60, s3, 31
	v_writelane_b32 v254, s5, 3
	s_lshr_b32 s4, s33, 29
	s_add_i32 s5, s2, s4
	s_ashr_i32 s4, s5, 3
	s_and_b32 s5, s5, -8
	s_sub_i32 s5, s2, s5
	s_add_u32 s6, s8, 0x8200
	s_addc_u32 s7, s9, 0
	s_add_u32 s76, s8, 0x8400
	s_addc_u32 s77, s9, 0
	s_add_u32 s78, s8, 0x8500
	v_writelane_b32 v254, s6, 4
	s_addc_u32 s79, s9, 0
	s_mov_b32 s16, 0x41c00000
	v_writelane_b32 v254, s7, 5
	s_add_u32 s6, s8, 0x8600
	s_addc_u32 s7, s9, 0
	v_writelane_b32 v254, s6, 6
	s_mov_b32 s18, 0x41d00000
	v_mbcnt_lo_u32_b32 v0, -1, 0
	v_writelane_b32 v254, s7, 7
	s_add_u32 s6, s8, 0x8700
	s_addc_u32 s7, s9, 0
	v_writelane_b32 v254, s6, 8
	v_mov_b32_e32 v1, 0
	v_mov_b32_e32 v224, 1
	v_writelane_b32 v254, s7, 9
	s_add_u32 s6, s8, 0x8800
	s_addc_u32 s7, s9, 0
	v_writelane_b32 v254, s6, 10
	v_mov_b32_e32 v234, 0x260
	v_mov_b32_e32 v235, 0x3c23d70a
	v_writelane_b32 v254, s7, 11
	s_add_u32 s6, s8, 0x8900
	s_addc_u32 s7, s9, 0
	v_writelane_b32 v254, s6, 12
	s_mov_b32 s17, 0x41c80000
	s_mov_b32 s19, 0x41d80000
	v_writelane_b32 v254, s7, 13
	s_add_u32 s6, s8, 0x8a00
	s_addc_u32 s7, s9, 0
	v_writelane_b32 v254, s6, 14
	v_mov_b32_e32 v236, 0x358637bd
	v_mov_b64_e32 v[226:227], 0x600
	v_writelane_b32 v254, s7, 15
	s_add_u32 s6, s8, 0x8b00
	s_addc_u32 s7, s9, 0
	v_writelane_b32 v254, s6, 16
	v_mov_b64_e32 v[228:229], 0x5ff
	v_mov_b32_e32 v225, 0x3e38aa3b
	v_writelane_b32 v254, s7, 17
	s_add_u32 s6, s8, 0x8c00
	s_addc_u32 s7, s9, 0
	v_writelane_b32 v254, s6, 18
	v_mov_b32_e32 v230, 0x3db504f3
	v_mbcnt_hi_u32_b32 v240, -1, v0
	v_writelane_b32 v254, s7, 19
	s_add_u32 s6, s8, 0x8d00
	s_addc_u32 s7, s9, 0
	v_writelane_b32 v254, s6, 20
	v_mov_b32_e32 v241, 0x42800000
	v_mov_b32_e32 v242, 0x42000000
	v_writelane_b32 v254, s7, 21
	s_add_u32 s6, s8, 0x8e00
	s_addc_u32 s7, s9, 0
	v_writelane_b32 v254, s6, 22
	v_mov_b32_e32 v243, 0x3fb8aa3b
	v_mov_b32_e32 v244, 0xff800000
	v_writelane_b32 v254, s7, 23
	s_add_u32 s6, s8, 0x8f00
	s_addc_u32 s7, s9, 0
	v_writelane_b32 v254, s6, 24
	v_mov_b32_e32 v245, 0xc8000
	v_mov_b64_e32 v[212:213], 0x200
	v_writelane_b32 v254, s7, 25
	s_add_u32 s6, s8, 0x9000
	s_addc_u32 s7, s9, 0
	v_writelane_b32 v254, s6, 26
	v_mov_b64_e32 v[214:215], 0x1ff
	v_mov_b64_e32 v[238:239], 0xb00
	v_writelane_b32 v254, s7, 27
	s_add_u32 s6, s8, 0x9100
	s_addc_u32 s7, s9, 0
	v_writelane_b32 v254, s6, 28
	v_mov_b64_e32 v[218:219], 0xaff
	s_movk_i32 s61, 0x3200
	v_writelane_b32 v254, s7, 29
	s_add_u32 s6, s8, 0x9200
	s_addc_u32 s7, s9, 0
	v_writelane_b32 v254, s6, 30
	s_movk_i32 s62, 0x1000
	s_mov_b32 s64, 0xc2fc0000
	v_writelane_b32 v254, s7, 31
	s_add_u32 s6, s8, 0x9300
	s_addc_u32 s7, s9, 0
	v_writelane_b32 v254, s6, 32
	s_cmp_eq_u32 s52, 15
	s_movk_i32 s65, 0x110
	v_writelane_b32 v254, s7, 33
	s_cselect_b64 s[6:7], -1, 0
	v_writelane_b32 v254, s6, 34
	s_cmp_eq_u32 s52, 14
	s_movk_i32 s66, 0x600
	v_writelane_b32 v254, s7, 35
	s_cselect_b64 s[6:7], -1, 0
	v_writelane_b32 v254, s6, 36
	s_cmp_eq_u32 s52, 13
	s_mov_b32 s67, 0x40c00000
	v_writelane_b32 v254, s7, 37
	s_cselect_b64 s[6:7], -1, 0
	v_writelane_b32 v254, s6, 38
	s_cmp_eq_u32 s52, 12
	s_mov_b32 s68, 0xf800000
	v_writelane_b32 v254, s7, 39
	s_cselect_b64 s[6:7], -1, 0
	v_writelane_b32 v254, s6, 40
	s_cmp_eq_u32 s52, 11
	s_mov_b32 s69, 0x42a00000
	v_writelane_b32 v254, s7, 41
	s_cselect_b64 s[6:7], -1, 0
	v_writelane_b32 v254, s6, 42
	s_cmp_eq_u32 s52, 10
	s_movk_i32 s71, 0x7fff
	v_writelane_b32 v254, s7, 43
	s_cselect_b64 s[6:7], -1, 0
	v_writelane_b32 v254, s6, 44
	s_cmp_eq_u32 s52, 9
	s_mov_b32 s72, 0x5040100
	v_writelane_b32 v254, s7, 45
	s_cselect_b64 s[6:7], -1, 0
	v_writelane_b32 v254, s6, 46
	s_cmp_eq_u32 s52, 8
	s_movk_i32 s73, 0x2c00
	v_writelane_b32 v254, s7, 47
	s_cselect_b64 s[6:7], -1, 0
	v_writelane_b32 v254, s6, 48
	s_cmp_eq_u32 s52, 7
	s_mov_b32 s21, 0
	v_writelane_b32 v254, s7, 49
	s_cselect_b64 s[6:7], -1, 0
	v_writelane_b32 v254, s6, 50
	s_cmp_eq_u32 s52, 6
	s_mov_b64 s[30:31], 0x80
	v_writelane_b32 v254, s7, 51
	s_cselect_b64 s[6:7], -1, 0
	v_writelane_b32 v254, s6, 52
	s_cmp_eq_u32 s52, 5
	s_nop 0
	v_writelane_b32 v254, s7, 53
	s_cselect_b64 s[6:7], -1, 0
	v_writelane_b32 v254, s6, 54
	s_cmp_eq_u32 s52, 4
	s_nop 0
	v_writelane_b32 v254, s7, 55
	s_cselect_b64 s[6:7], -1, 0
	v_writelane_b32 v254, s6, 56
	s_cmp_eq_u32 s52, 3
	s_nop 0
	v_writelane_b32 v254, s7, 57
	s_cselect_b64 s[6:7], -1, 0
	v_writelane_b32 v254, s6, 58
	s_cmp_eq_u32 s52, 2
	s_nop 0
	v_writelane_b32 v254, s7, 59
	s_cselect_b64 s[6:7], -1, 0
	v_writelane_b32 v254, s6, 60
	s_cmp_eq_u32 s52, 1
	s_nop 0
	v_writelane_b32 v254, s7, 61
	s_cselect_b64 s[6:7], -1, 0
	v_writelane_b32 v254, s6, 62
	s_cmp_eq_u32 s52, 0
	s_nop 0
	v_writelane_b32 v254, s7, 63
;     __device__ __forceinline__ bool next(int i, Unit& u) const { if (i) return false; u.pm = pm; u.pn = pn; return true; }
;     __host__ __device__ bool next(int i, Unit& u) const {
;         const long L = (long)i * G + c; if (L >= nwg) return false;
;         int wgid = (int)L; { const int q = nwg / NXCD, r = nwg % NXCD, xcd = wgid % NXCD, off = wgid / NXCD; wgid = (xcd < r ? xcd * (q + 1) : r * (q + 1) + (xcd - r) * q) + off; }
;         const int nig = WGM * nN, gid = wgid / nig, fm = gid * WGM, gsz = (nM - fm) < WGM ? (nM - fm) : WGM;
;         u.pm = fm + ((wgid % nig) % gsz); u.pn = (wgid % nig) / gsz; return true;
;     }
; template <class Epi, class Sched, bool ALIGN_EPI = false, bool SP2 = false>
; __device__ __forceinline__ void gemm_phase(PG8_LAS unsigned char* lds, const Gemm g, const Sched& S, const Epi& E) {
;     ...
;     const char* cA = (const char*)g.A + (size_t)cur.pm * tstep; const char* cB = (const char*)g.Bt + (size_t)cur.pn * tstep;
	s_cselect_b64 s[6:7], -1, 0
	v_writelane_b32 v255, s6, 0
	s_nop 1
	v_writelane_b32 v255, s7, 1
	s_lshl_b32 s6, s52, 8
	s_add_u32 s6, s10, s6
	s_addc_u32 s7, s11, 0
	s_add_u32 s10, s6, 0x1400
	s_addc_u32 s11, s7, 0
	v_writelane_b32 v255, s10, 2
	s_add_u32 s6, s6, 0x2400
	s_addc_u32 s7, s7, 0
	v_writelane_b32 v255, s11, 3
	v_writelane_b32 v255, s6, 4
	s_nop 1
	v_writelane_b32 v255, s7, 5
	s_add_u32 s6, s8, 0xb400
	s_addc_u32 s7, s9, 0
	v_writelane_b32 v255, s6, 6
	s_nop 1
	v_writelane_b32 v255, s7, 7
	s_add_u32 s6, s8, 0xb500
	s_addc_u32 s7, s9, 0
	v_writelane_b32 v255, s6, 8
	s_lshl_b32 s20, s2, 3
	s_lshl_b32 s22, s3, 4
	v_writelane_b32 v255, s7, 9
	s_lshl_b32 s6, s2, 4
	s_cmpk_lt_i32 s2, 0x200
	v_writelane_b32 v255, s6, 10
	s_cselect_b64 s[6:7], -1, 0
	v_writelane_b32 v255, s6, 11
	s_nop 1
	v_writelane_b32 v255, s7, 12
	s_lshl_b32 s6, s5, 6
	s_cmpk_lt_i32 s2, 0xb00
	s_cselect_b64 s[8:9], -1, 0
	s_cmp_lt_i32 s5, 0
	s_mul_i32 s7, s5, 0x41
	s_cselect_b32 s6, s7, s6
	s_movk_i32 s7, 0xc9
	v_writelane_b32 v255, s8, 13
	s_cselect_b32 s7, s7, 0xc8
	s_mul_i32 s7, s5, s7
	v_writelane_b32 v255, s9, 14
	s_movk_i32 s8, 0x161
	s_cselect_b32 s8, s8, 0x160
	s_add_i32 s7, s7, s4
	s_mul_hi_i32 s9, s7, 0x51eb851f
	s_lshr_b32 s10, s9, 31
	s_ashr_i32 s9, s9, 6
	s_add_i32 s9, s9, s10
	s_mul_i32 s10, s9, 0xc8
	s_sub_i32 s7, s7, s10
	s_bfe_u32 s10, s7, 0x3001c
	s_add_i32 s10, s7, s10
	s_and_b32 s11, s10, 0xfff8
	s_add_i32 s6, s6, s4
	s_sub_i32 s7, s7, s11
	s_ashr_i32 s11, s6, 31
	s_lshr_b32 s11, s11, 26
	s_mul_i32 s5, s5, s8
	s_add_i32 s11, s6, s11
	s_add_i32 s5, s5, s4
	s_and_b32 s12, s11, 0xffc0
	s_mul_hi_i32 s4, s5, 0x2e8ba2e9
	s_sub_i32 s6, s6, s12
	s_lshr_b32 s8, s4, 31
	s_ashr_i32 s4, s4, 6
	s_bfe_i32 s12, s6, 0x80000
	s_add_i32 s8, s4, s8
	s_bfe_u32 s12, s12, 0x3000c
	s_mul_i32 s4, s8, 0x160
	s_add_i32 s12, s6, s12
	s_sub_i32 s4, s5, s4
	s_and_b32 s13, s12, 0xf8
	s_bfe_u32 s5, s4, 0x3001c
	s_sub_i32 s6, s6, s13
	s_add_i32 s13, s4, s5
	s_and_b32 s5, s13, 0xfff8
	s_sub_i32 s14, s4, s5
	s_lshl_b32 s4, s9, 3
	s_sext_i32_i16 s5, s10
	s_sext_i32_i16 s7, s7
	s_add_i32 s24, s4, s7
	s_ashr_i32 s4, s5, 3
	v_writelane_b32 v255, s4, 15
	s_lshr_b32 s4, s5, 3
	s_bfe_i64 s[4:5], s[4:5], 0x100000
	s_lshl_b64 s[4:5], s[4:5], 20
	v_writelane_b32 v255, s4, 16
	s_sext_i32_i8 s6, s6
	s_ashr_i32 s25, s24, 31
	v_writelane_b32 v255, s5, 17
	s_ashr_i32 s4, s11, 6
	s_bfe_i32 s5, s12, 0x80000
	s_lshl_b32 s4, s4, 3
	s_sext_i32_i16 s5, s5
	s_add_i32 s26, s4, s6
	s_ashr_i32 s4, s5, 3
	v_writelane_b32 v255, s4, 18
	s_lshr_b32 s4, s5, 3
	s_bfe_i64 s[4:5], s[4:5], 0x100000
	s_lshl_b64 s[4:5], s[4:5], 20
	v_writelane_b32 v255, s4, 19
	s_sext_i32_i16 s6, s14
	s_ashr_i32 s27, s26, 31
	v_writelane_b32 v255, s5, 20
	s_lshl_b32 s4, s8, 3
	s_sext_i32_i16 s5, s13
	s_add_i32 s28, s4, s6
	s_ashr_i32 s4, s5, 3
	v_writelane_b32 v255, s4, 21
	s_lshr_b32 s4, s5, 3
	s_bfe_i64 s[4:5], s[4:5], 0x100000
	s_lshl_b64 s[4:5], s[4:5], 20
	v_writelane_b32 v255, s4, 22
	s_ashr_i32 s29, s28, 31
	s_ashr_i32 s55, s54, 31
	v_writelane_b32 v255, s5, 23
	s_mov_b32 s4, 1
	v_writelane_b32 v255, s4, 24
	v_writelane_b32 v255, s20, 25
	s_add_i32 s4, s20, s54
	v_writelane_b32 v255, s4, 26
	s_add_i32 s4, 0, 0x22020
	v_writelane_b32 v255, s4, 27
	s_add_i32 s4, 0, 0x22024
	v_writelane_b32 v255, s4, 28
	s_add_i32 s4, 0, 0x19800
	v_writelane_b32 v255, s4, 29
	s_mov_b32 s4, 0
	v_writelane_b32 v255, s4, 30
	s_mov_b32 s4, s24
	v_writelane_b32 v255, s4, 31
	s_mov_b32 s6, 2.0
	s_mov_b32 s8, 0x41000000
	v_writelane_b32 v255, s5, 32
	s_lshl_b64 s[4:5], s[24:25], 20
	v_writelane_b32 v255, s4, 33
	s_lshl_b64 s[24:25], s[54:55], 12
	s_mov_b32 s10, 0x41200000
	v_writelane_b32 v255, s5, 34
	s_mov_b32 s4, s26
	v_writelane_b32 v255, s4, 35
	s_mov_b32 s12, 0x41800000
	s_mov_b32 s14, 0x41900000
	v_writelane_b32 v255, s5, 36
	s_lshl_b64 s[4:5], s[26:27], 20
	v_writelane_b32 v255, s4, 37
	s_lshl_b32 s91, s3, 11
	s_mov_b32 s7, 0x40400000
	v_writelane_b32 v255, s5, 38
	s_mov_b32 s4, s28
	v_writelane_b32 v255, s4, 39
	s_mov_b32 s9, 0x41100000
	s_mov_b32 s11, 0x41300000
	v_writelane_b32 v255, s5, 40
	s_lshl_b64 s[4:5], s[28:29], 20
	v_writelane_b32 v255, s4, 41
	s_mov_b32 s13, 0x41880000
	s_mov_b32 s15, 0x41980000
	v_writelane_b32 v255, s5, 42
	s_lshl_b64 s[4:5], s[54:55], 2
	v_writelane_b32 v255, s4, 43
	s_add_i32 s63, 0, 0x22000
	s_add_i32 s70, 0, 0x11000
	v_writelane_b32 v255, s5, 44
	s_lshl_b64 s[4:5], s[54:55], 13
	v_writelane_b32 v255, s4, 45
	s_mov_b32 s55, s22
	s_mov_b64 s[28:29], 0x80000
	v_writelane_b32 v255, s5, 46
	v_writelane_b32 v255, s74, 47
	s_nop 1
	v_writelane_b32 v255, s75, 48
	v_writelane_b32 v255, s76, 49
	s_nop 1
	v_writelane_b32 v255, s77, 50
	v_writelane_b32 v255, s78, 51
	s_nop 1
	v_writelane_b32 v255, s79, 52
	v_writelane_b32 v255, s55, 53
	v_writelane_b32 v255, s91, 54
	s_branch .LBB0_128

; template <class Epi, class Sched, bool ALIGN_EPI = false, bool SP2 = false>
; __device__ __forceinline__ void gemm_phase(PG8_LAS unsigned char* lds, const Gemm g, const Sched& S, const Epi& E) {
;     int tid = threadIdx.x; asm volatile("" : "+v"(tid)); const int wid = __builtin_amdgcn_readfirstlane(tid >> 6), lane = tid & 63, wr = wid >> 2, wc = wid & 3, fr = lane & 15, fq = lane >> 4;
;     const int K = g.K, nt = K / BK;
;     unsigned voffA[2], voffB[2];
; #pragma unroll
;     for (int i = 0; i < 2; ++i) { int R, C; stage_rc(tid * 16 + i * 8192, R, C); const int Rb = Epi::PERM ? ((R & ~31) + perm32(R & 31)) : R;
;         voffA[i] = (unsigned)(R * K + C) * 2u; voffB[i] = (unsigned)(Rb * K + C) * 2u; }
;     const size_t kstep = (size_t)(BK * 2);
;     const size_t hstep = (size_t)HALF * K * 2;
;     const size_t tstep = 2 * hstep;
;     const unsigned ldsw = (unsigned)wid * 1024u;
;     const int aoff = lds_byte(wr * 64 + fr, fq * 8), boff = lds_byte(wc * 32 + fr, fq * 8);
;     ...
;     Unit cur, nxt; int ui = 0;
;     if (!S.next(0, cur)) return;
;     f32x4 acc[2][2][4][2];
; #pragma unroll
;     for (int a = 0; a < 2; ++a)
; #pragma unroll
;         for (int b = 0; b < 2; ++b)
; #pragma unroll
;             for (int m = 0; m < 4; ++m)
; #pragma unroll
;                 for (int n = 0; n < 2; ++n) acc[a][b][m][n] = (f32x4){0.f, 0.f, 0.f, 0.f};
;     bf16x8 At[4][2], B0[2][2], B1[2][2];
;     const char* cA = (const char*)g.A + (size_t)cur.pm * tstep; const char* cB = (const char*)g.Bt + (size_t)cur.pn * tstep;
;     S.a_ready(cur);
;     if constexpr (SP2) {
;         PG8_STAGE(PG8_SB(0, 0), cB, voffB); PG8_STAGE(PG8_SB(0, 1), cB + hstep, voffB); PG8_STAGE(PG8_SA(0, 0), cA, voffA); PG8_STAGE(PG8_SA(0, 1), cA + hstep, voffA);
;         if (wr == 1) PG8_BAR;
;         PG8_WAIT_V(2); PG8_BAR;
;         PG8_STAGE(PG8_SB(1, 0), cB + kstep, voffB); PG8_STAGE(PG8_SA(1, 0), cA + kstep, voffA); PG8_STAGE(PG8_SB(1, 1), cB + hstep + kstep, voffB);
; __global__ void __launch_bounds__(NTHR, 2) fwd(Args args) {
;     ...
;         if (XEN(1) && IN_PH()) for (int rep = 0; rep < XREP(1); ++rep) { PIN_TID();
;             pg8::Gemm g{XN, WIN + (size_t)l * INW * DM, M, INW, DM}; pg8::StaticOrder S; S.init(M, INW - 256 * XTAIL, G, (int)blockIdx.x);
;             pg8::EpiProj E{PROJ, INW, RS};
;             pg8::gemm_phase<pg8::EpiProj, pg8::StaticOrder, PG8ALIGN, PG8SP2>(lds, g, S, E);
.LBB0_128:
	s_mov_b32 s99, 0
	v_readlane_b32 s20, v255, 24
	s_cmp_le_i32 s58, s20
	s_cselect_b64 s[4:5], -1, 0
	s_cmp_lt_i32 s20, s59
	s_cselect_b64 s[22:23], -1, 0
	s_and_b64 s[22:23], s[4:5], s[22:23]
	s_andn2_b64 vcc, exec, s[22:23]
	s_cbranch_vccnz .LBB0_145
.Lxtail_p1body:
	v_readlane_b32 s22, v254, 2
	v_mov_b32_e32 v0, v232
	s_mov_b32 s38, 21
	s_mov_b32 s36, 21
	s_mov_b32 s26, 21
	s_mov_b32 s34, 21
	v_mov_b32_e32 v10, v232
	v_readlane_b32 s23, v254, 3
	s_andn2_b64 vcc, exec, s[22:23]
	v_readfirstlane_b32 s22, v10
	s_cbranch_vccnz .LBB0_145
	s_ashr_i32 s39, s38, 31
	s_lshl_b64 s[38:39], s[38:39], 3
	s_add_u32 s38, s0, s38
	s_addc_u32 s39, s1, s39
	s_load_dwordx2 s[38:39], s[38:39], 0x0
	v_lshlrev_b32_e32 v0, 4, v10
	v_add_u32_e32 v2, 0x2000, v0
	v_ashrrev_i32_e32 v3, 31, v2
	v_lshrrev_b32_e32 v3, 22, v3
	s_waitcnt lgkmcnt(0)
	s_add_u32 s55, s38, 0x18e00000
	s_addc_u32 s58, s39, 0
	s_ashr_i32 s37, s36, 31
	s_lshl_b64 s[36:37], s[36:37], 3
	s_add_u32 s36, s0, s36
	s_addc_u32 s37, s1, s37
	s_load_dwordx2 s[36:37], s[36:37], 0x0
	v_readlane_b32 s20, v255, 30
	v_add_u32_e32 v3, v2, v3
	s_mul_i32 s20, s20, 0xc80000
	v_ashrrev_i32_e32 v11, 10, v3
	s_lshl_b64 s[38:39], s[20:21], 1
	v_mul_i32_i24_e32 v3, 0x400, v11
	s_waitcnt lgkmcnt(0)
	s_add_u32 s20, s36, s38
	v_sub_u32_e32 v2, v2, v3
	s_addc_u32 s23, s37, s39
	v_lshrrev_b32_e32 v3, 4, v2
	s_add_u32 s20, s20, 0x200000
	v_bitop3_b32 v2, v3, v2, 32 bitop3:0x6c
	s_addc_u32 s59, s23, 0
	s_ashr_i32 s27, s26, 31
	v_ashrrev_i32_e32 v3, 31, v2
	s_lshl_b64 s[26:27], s[26:27], 3
	v_lshrrev_b32_e32 v3, 26, v3
	s_add_u32 s26, s0, s26
	v_add_u32_e32 v3, v2, v3
	v_lshlrev_b32_e32 v4, 3, v11
	s_addc_u32 s27, s1, s27
	s_ashr_i32 s35, s34, 31
	v_ashrrev_i32_e32 v12, 6, v3
	v_and_b32_e32 v4, -16, v4
	s_lshl_b64 s[34:35], s[34:35], 3
	v_add_u32_e32 v4, v12, v4
	s_add_u32 s36, s0, s34
	v_and_b32_e32 v5, 3, v12
	s_mov_b32 s34, 0xfffe0
	v_lshrrev_b32_e32 v6, 2, v4
	v_lshlrev_b32_e32 v7, 1, v4
	v_and_b32_e32 v3, 0xc0, v3
	v_and_or_b32 v5, v4, s34, v5
	v_and_b32_e32 v6, 4, v6
	v_and_b32_e32 v7, 24, v7
	v_sub_u32_e32 v2, v2, v3
	v_or3_b32 v5, v5, v6, v7
	v_lshlrev_b32_e32 v6, 5, v11
	v_ashrrev_i16_sdwa v2, v224, sext(v2) dst_sel:DWORD dst_unused:UNUSED_PAD src0_sel:DWORD src1_sel:BYTE_0
	v_and_b32_e32 v6, 32, v6
	v_bfe_i32 v13, v2, 0, 16
	v_add_lshl_u32 v2, v6, v13, 1
	v_lshl_add_u32 v130, v5, 12, v2
	v_lshl_add_u32 v132, v4, 12, v2
	v_bfe_i32 v2, v10, 27, 1
	v_lshrrev_b32_e32 v2, 22, v2
	v_add_u32_e32 v2, v0, v2
	v_and_b32_e32 v2, 0xfffffc00, v2
	v_sub_u32_e32 v0, v0, v2
	v_lshrrev_b32_e32 v2, 4, v0
	v_ashrrev_i32_e32 v3, 31, v10
	v_bitop3_b32 v0, v2, v0, 32 bitop3:0x6c
	v_lshrrev_b32_e32 v3, 26, v3
	v_ashrrev_i32_e32 v2, 31, v0
	v_add_u32_e32 v3, v10, v3
	v_lshrrev_b32_e32 v2, 26, v2
	v_ashrrev_i32_e32 v15, 6, v3
	v_add_u32_e32 v2, v0, v2
	v_lshlrev_b32_e32 v3, 3, v15
	v_ashrrev_i32_e32 v14, 6, v2
	v_and_b32_e32 v3, -16, v3
	v_add_u32_e32 v3, v14, v3
	v_and_b32_e32 v4, 3, v14
	v_lshrrev_b32_e32 v5, 2, v3
	v_lshlrev_b32_e32 v6, 1, v3
	v_and_b32_e32 v2, 0xc0, v2
	s_addc_u32 s37, s1, s35
	s_ashr_i32 s42, s22, 6
	v_and_or_b32 v4, v3, s34, v4
	v_and_b32_e32 v5, 4, v5
	v_and_b32_e32 v6, 24, v6
	v_sub_u32_e32 v0, v0, v2
	s_ashr_i32 s23, s22, 8
	s_lshl_b32 s74, s42, 10
	v_or3_b32 v4, v4, v5, v6
	v_lshlrev_b32_e32 v5, 5, v15
	v_ashrrev_i16_sdwa v0, v224, sext(v0) dst_sel:DWORD dst_unused:UNUSED_PAD src0_sel:DWORD src1_sel:BYTE_0
	v_readlane_b32 s34, v255, 16
	v_and_b32_e32 v5, 32, v5
	v_bfe_i32 v16, v0, 0, 16
	v_readlane_b32 s35, v255, 17
	s_add_u32 s34, s20, s34
	v_add_lshl_u32 v2, v5, v16, 1
	s_addc_u32 s35, s59, s35
	s_add_i32 s75, s74, 0
	v_lshl_add_u32 v0, v4, 12, v2
	s_add_i32 m0, s75, 0x10000
	v_lshl_add_u32 v134, v3, 12, v2
	global_load_lds_dwordx4 v0, s[34:35]
	s_add_i32 m0, s75, 0x12000
	s_add_u32 s38, s34, 0x80000
	global_load_lds_dwordx4 v130, s[34:35]
	s_addc_u32 s39, s35, 0
	s_add_i32 m0, s75, 0x14000
	v_mov_b32_e32 v131, v1
	global_load_lds_dwordx4 v0, s[38:39]
	s_add_i32 m0, s75, 0x16000
	v_mov_b32_e32 v135, v1
	global_load_lds_dwordx4 v130, s[38:39]
	v_readlane_b32 s38, v255, 33
	v_readlane_b32 s39, v255, 34
	s_add_u32 s48, s55, s38
	s_addc_u32 s49, s58, s39
	s_add_i32 s76, s75, 0x2000
	s_mov_b32 m0, s75
	s_add_u32 s38, s48, 0x80000
	global_load_lds_dwordx4 v134, s[48:49]
	s_mov_b32 m0, s76
	s_addc_u32 s39, s49, 0
	s_add_i32 s77, s75, 0x4000
	global_load_lds_dwordx4 v132, s[48:49]
	s_mov_b32 m0, s77
	s_add_i32 s78, s75, 0x6000
	global_load_lds_dwordx4 v134, s[38:39]
	s_mov_b32 m0, s78
	v_mov_b32_e32 v133, v1
	global_load_lds_dwordx4 v132, s[38:39]
	s_load_dwordx2 s[40:41], s[26:27], 0x0
	s_load_dwordx2 s[38:39], s[36:37], 0x0
	s_cmp_eq_u32 s23, 1
	v_lshl_add_u64 v[8:9], s[34:35], 0, v[0:1]
	v_lshl_add_u64 v[6:7], s[34:35], 0, v[130:131]
	v_lshl_add_u64 v[2:3], s[48:49], 0, v[134:135]
	s_cselect_b64 s[26:27], -1, 0
	s_cmp_lg_u32 s23, 1
	v_lshl_add_u64 v[4:5], s[48:49], 0, v[132:133]
	s_cbranch_scc1 .LBB0_132
	s_barrier

; #define PG8_WAIT_V(n) asm volatile("s_waitcnt vmcnt(" #n ")" ::: "memory")
; #define PG8_BAR __builtin_amdgcn_s_barrier()
; #define PIN_TID() int tid = threadIdx.x; asm volatile("" : "+v"(tid)); const int lane = tid & 63, wid = __builtin_amdgcn_readfirstlane(tid >> 6), gw = blockIdx.x * NWAVES + wid; (void)lane; (void)gw
; #define SEAM() do { if (lo <= ph && ph + 1 < hi) { xcd_barrier(bar); if (XREP(10) > 1) xcd_barrier(bar); } ++ph; } while (0)
; template <class Epi, class Sched, bool ALIGN_EPI = false, bool SP2 = false>
; __device__ __forceinline__ void gemm_phase(PG8_LAS unsigned char* lds, const Gemm g, const Sched& S, const Epi& E) {
;     ...
;     PG8_WAIT_V(0);
;     if constexpr (!ALIGN_EPI) { if (wr == 0) PG8_BAR; }
;     PG8_BAR;
; __global__ void __launch_bounds__(NTHR, 2) fwd(Args args) {
;     ...
;         SEAM();
;         if (XEN(3) && IN_PH()) for (int rep = 0; rep < XREP(3); ++rep) { PIN_TID();
.LBB0_144:
	s_load_dwordx2 s[58:59], s[0:1], 0xb0
	s_waitcnt vmcnt(0)
	v_readlane_b32 s74, v255, 47
	v_readlane_b32 s76, v255, 49
	v_readlane_b32 s78, v255, 51
	v_readlane_b32 s75, v255, 48
	v_readlane_b32 s77, v255, 50
	v_readlane_b32 s79, v255, 52
	v_readlane_b32 s55, v255, 53
	s_barrier
	s_cmp_eq_u32 s98, 0
	s_cbranch_scc1 .LBB0_145
	s_mov_b32 s98, 0
	v_readlane_b32 s80, v255, 57
	v_readlane_b32 s81, v255, 58
	v_readlane_b32 s82, v255, 59
	v_readlane_b32 s83, v255, 60
	v_readlane_b32 s84, v255, 61
	v_readlane_b32 s85, v255, 62
	s_nop 1
	v_writelane_b32 v255, s80, 15
	v_writelane_b32 v255, s81, 16
	v_writelane_b32 v255, s82, 17
	v_writelane_b32 v255, s83, 31
	v_writelane_b32 v255, s84, 33
	v_writelane_b32 v255, s85, 34
	v_mov_b32_e32 v226, 0x600
	v_mov_b32_e32 v227, 0
	v_mov_b32_e32 v228, 0x5ff
	v_mov_b32_e32 v229, 0
	s_waitcnt lgkmcnt(0)
	s_branch .Lxtail_p3_reentry

; #define LAS __attribute__((address_space(3)))
; __device__ __forceinline__ void qk_norms(LAS unsigned char* lds, const bfu* PROJ, unsigned* nw) {
;     int tid = threadIdx.x; asm volatile("" : "+v"(tid)); const int lane = tid & 63, wid = __builtin_amdgcn_readfirstlane(tid >> 6);
;     const int gw = blockIdx.x * NWAVES + wid, NGW = gridDim.x * NWAVES;
;     float m0[3] = {0.f, 0.f, 0.f}, m1[3] = {0.f, 0.f, 0.f};
;     for (int mb = gw; mb < M; mb += 4 * NGW) {
;         v4u w[4][3];
; #pragma unroll
;         for (int r = 0; r < 4; ++r) { const int m = mb + r * NGW; const bfu* rp = PROJ + (size_t)(m < M ? m : mb) * INW + C_DQ + lane * 8;
.Lxtail_p3_reentry:
	v_mov_b32_e32 v48, v232
	s_mov_b32 s4, 21
	s_ashr_i32 s5, s4, 31
	s_lshl_b64 s[4:5], s[4:5], 3
	s_add_u32 s4, s0, s4
	s_addc_u32 s5, s1, s5
	s_load_dwordx2 s[4:5], s[4:5], 0x0
	s_mov_b32 s26, 21
	v_mov_b32_e32 v46, v232
	v_readlane_b32 s22, v255, 25
	v_readfirstlane_b32 s20, v46
	s_ashr_i32 s20, s20, 6
	s_add_i32 s22, s20, s22
	v_and_b32_e32 v47, 63, v46
	v_mov_b32_e32 v53, 0
	s_cmpk_gt_i32 s22, 0x3fff
	v_mov_b32_e32 v54, 0
	v_mov_b32_e32 v52, 0
	v_mov_b32_e32 v50, 0
	v_mov_b32_e32 v49, 0
	v_mov_b32_e32 v51, 0
	s_cbranch_scc1 .LBB0_223
	s_cmp_lg_u32 s99, 0
	s_cbranch_scc1 .LBB0_223
	s_ashr_i32 s27, s26, 31
	v_and_b32_e32 v3, 64, v240
	s_lshl_b64 s[26:27], s[26:27], 3
	v_xor_b32_e32 v2, 1, v240
	v_add_u32_e32 v3, 64, v3
	s_add_u32 s26, s0, s26
	v_cmp_lt_i32_e32 vcc, v2, v3
	s_addc_u32 s27, s1, s27
	s_load_dwordx2 s[26:27], s[26:27], 0x0
	v_cndmask_b32_e32 v2, v240, v2, vcc
	v_lshlrev_b32_e32 v55, 2, v2
	v_xor_b32_e32 v2, 2, v240
	v_cmp_lt_i32_e32 vcc, v2, v3
	v_lshlrev_b32_e32 v0, 3, v47
	s_waitcnt lgkmcnt(0)
	s_add_u32 s40, s26, 0x1ce00000
	v_cndmask_b32_e32 v2, v240, v2, vcc
	v_lshlrev_b32_e32 v56, 2, v2
	v_xor_b32_e32 v2, 4, v240
	v_cmp_lt_i32_e32 vcc, v2, v3
	s_addc_u32 s41, s27, 0
	v_mov_b32_e32 v52, 0
	v_cndmask_b32_e32 v2, v240, v2, vcc
	v_lshlrev_b32_e32 v57, 2, v2
	v_lshlrev_b32_e32 v0, 1, v0
	v_mov_b32_e32 v54, 0
	v_mov_b32_e32 v53, 0
	v_mov_b32_e32 v51, 0
	v_mov_b32_e32 v49, 0
	v_mov_b32_e32 v50, 0
	s_branch .LBB0_204

; __device__ __forceinline__ void publish(unsigned* word) {
;     asm volatile("s_waitcnt vmcnt(0)" ::: "memory"); __syncthreads();
;     if (threadIdx.x == 0) __hip_atomic_fetch_add(word, 1u, __ATOMIC_RELAXED, __HIP_MEMORY_SCOPE_AGENT);
; __global__ void __launch_bounds__(NTHR, 2) fwd(Args args) {
;     ...
;             qk_norms(lds, PROJ, cw + 64 * 15); publish(cw + 64 * 14);
.LBB0_227:
	s_or_b64 exec, exec, s[34:35]
	s_waitcnt vmcnt(0)
	s_barrier
	s_and_saveexec_b64 s[34:35], s[74:75]
	s_cbranch_execz .LBB0_230
	s_mov_b64 s[36:37], exec
	v_mbcnt_lo_u32_b32 v0, s36, 0
	v_mbcnt_hi_u32_b32 v0, s37, v0
	v_cmp_eq_u32_e32 vcc, 0, v0
	s_and_b64 s[22:23], exec, vcc
	s_mov_b64 exec, s[22:23]
	s_cbranch_execz .LBB0_230
	s_cmp_lg_u32 s99, 0
	s_cbranch_scc1 .Lxtail_skip_pub
	s_bcnt1_i32_b64 s20, s[36:37]
	v_mov_b32_e32 v0, s20
	global_atomic_add v1, v0, s[4:5] offset:3840
.Lxtail_skip_pub:
.LBB0_230:
	s_or_b64 exec, exec, s[34:35]
	s_cmp_lg_u32 s99, 0
	s_cbranch_scc1 .Lxtail_after
	s_cmp_ge_u32 s2, 64
	s_cbranch_scc1 .Lxtail_none
	s_mov_b32 s98, 1
	s_mov_b32 s99, 1
	v_readlane_b32 s80, v255, 15
	v_readlane_b32 s81, v255, 16
	v_readlane_b32 s82, v255, 17
	v_readlane_b32 s83, v255, 31
	v_readlane_b32 s84, v255, 33
	v_readlane_b32 s85, v255, 34
	s_and_b32 s86, s2, 7
	s_lshl_b32 s86, s86, 3
	s_lshr_b32 s87, s2, 3
	s_add_i32 s86, s86, s87
	s_lshl_b32 s87, s86, 20
	v_writelane_b32 v255, s80, 57
	v_writelane_b32 v255, s81, 58
	v_writelane_b32 v255, s82, 59
	v_writelane_b32 v255, s83, 60
	v_writelane_b32 v255, s84, 61
	v_writelane_b32 v255, s85, 62
	s_mov_b32 s80, 24
	s_mov_b32 s81, 0x1800000
	s_mov_b32 s82, 0
	v_writelane_b32 v255, s80, 15
	v_writelane_b32 v255, s81, 16
	v_writelane_b32 v255, s82, 17
	v_writelane_b32 v255, s86, 31
	v_writelane_b32 v255, s87, 33
	v_writelane_b32 v255, s82, 34
	v_mov_b32_e32 v226, 0
	v_mov_b32_e32 v227, 0
	v_mov_b32_e32 v228, -1
	v_mov_b32_e32 v229, -1
	v_mov_b32_e32 v225, 0x3e38aa3b
	v_mov_b32_e32 v230, 0x3db504f3
	s_branch .Lxtail_p1body
.Lxtail_after:
	s_and_saveexec_b64 s[34:35], s[74:75]
	s_cbranch_execz .Lxtail_after2
	buffer_wbl2 sc1
	s_waitcnt vmcnt(0)
	v_mov_b32_e32 v0, 1
	global_atomic_add v1, v0, s[4:5] offset:3584

; #define PULL_ISSUE(hd) ((tid == 0) ? (int)__hip_atomic_fetch_add((hd), 1u, __ATOMIC_RELAXED, __HIP_MEMORY_SCOPE_AGENT) : 0)
; #define BCAST(v) ({ if (tid == 0) MISC[0] = (v); __syncthreads(); const int u__ = __builtin_amdgcn_readfirstlane(MISC[0]); __syncthreads(); u__; })
; __global__ void __launch_bounds__(NTHR, 2) fwd(Args args) {
;     ...
;             { int nx = PULL_ISSUE(cw);
;               for (;;) {
;                 const int u = BCAST(nx);
;                 if (u >= 768 + 96) break;
;                 nx = PULL_ISSUE(cw);
.Lxtail_none:
	v_mov_b32_e32 v16, 0
	v_cmp_eq_u32_e64 s[38:39], 0, v48
	s_and_saveexec_b64 s[34:35], s[38:39]
	s_cbranch_execz .LBB0_234
	s_mov_b64 s[40:41], exec
	v_mbcnt_lo_u32_b32 v0, s40, 0
	v_mbcnt_hi_u32_b32 v0, s41, v0
	v_cmp_eq_u32_e32 vcc, 0, v0
	s_and_saveexec_b64 s[36:37], vcc
	s_cbranch_execz .LBB0_233
	s_bcnt1_i32_b64 s20, s[40:41]
	v_mov_b32_e32 v2, s20
	global_atomic_add v2, v1, v2, s[26:27] sc0

; #define PULL_ISSUE(hd) ((tid == 0) ? (int)__hip_atomic_fetch_add((hd), 1u, __ATOMIC_RELAXED, __HIP_MEMORY_SCOPE_AGENT) : 0)
; __global__ void __launch_bounds__(NTHR, 2) fwd(Args args) {
;     ...
;             { int nx = PULL_ISSUE(cw + 64 * 12);
.LBB0_404:
	v_mov_b32_e32 v68, 0
	s_mov_b64 s[26:27], exec
	s_load_dwordx2 s[58:59], s[0:1], 0xb0
	v_readlane_b32 s74, v255, 47
	s_and_b64 s[22:23], s[26:27], s[38:39]
	v_readlane_b32 s75, v255, 48
	v_mov_b32_e32 v224, v217
	v_mov_b64_e32 v[226:227], 0x600
	v_mov_b64_e32 v[228:229], 0x5ff
	v_mov_b32_e32 v225, 0x3e38aa3b
	v_mov_b32_e32 v230, 0x3db504f3
	v_mov_b64_e32 v[238:239], 0xb00
	s_mov_b64 exec, s[22:23]
	s_cbranch_execz .LBB0_408
	s_mov_b64 s[36:37], exec
	v_mbcnt_lo_u32_b32 v0, s36, 0
	v_mbcnt_hi_u32_b32 v0, s37, v0
	v_cmp_eq_u32_e32 vcc, 0, v0
	s_and_saveexec_b64 s[34:35], vcc
	s_cbranch_execz .LBB0_407
	s_bcnt1_i32_b64 s20, s[36:37]
	v_mov_b32_e32 v2, s20
	global_atomic_add v2, v1, v2, s[4:5] offset:3328 sc0

; __device__ __forceinline__ const float* karg(int k) { int kk = k; asm volatile("" : "+s"(kk)); return ((const float* const __attribute__((address_space(4)))*)__builtin_amdgcn_kernarg_segment_ptr())[kk]; }
; #define PULL_ISSUE(hd) ((tid == 0) ? (int)__hip_atomic_fetch_add((hd), 1u, __ATOMIC_RELAXED, __HIP_MEMORY_SCOPE_AGENT) : 0)
; #define BCAST(v) ({ if (tid == 0) MISC[0] = (v); __syncthreads(); const int u__ = __builtin_amdgcn_readfirstlane(MISC[0]); __syncthreads(); u__; })
; __global__ void __launch_bounds__(NTHR, 2) fwd(Args args) {
;     ...
;             { int nx = PULL_ISSUE(cw + 64 * 12);
;               for (;;) {
;                 const int u = BCAST(nx);
;                 if (u >= 768 + 512) break;
;                 nx = PULL_ISSUE(cw + 64 * 12);
;                 if (u < 768) { wait_ge(cw + 128 + (u >> 6), 8u, cw + 192); ret_unit(lds, PROJ, RT, karg(3) + l * 768, CAT, u); }
;                 else sgu_unit(lds, PROJ, SGUW + (size_t)l * 65536, karg(9) + l * 512, karg(10) + l * 512, karg(12) + l * 512, CAT, u - 768);
;               } }
.LBB0_408:
	s_or_b64 exec, exec, s[26:27]
	s_and_saveexec_b64 s[34:35], s[74:75]
	s_cbranch_execz .Lxtail_wait_done
	s_mov_b32 s23, 0
.Lxtail_wait_loop:
	global_load_dword v0, v1, s[4:5] offset:3584 sc1
	s_waitcnt vmcnt(0)
	v_readfirstlane_b32 s22, v0
	s_cmp_ge_u32 s22, 64
	s_cbranch_scc1 .Lxtail_wait_ok
	s_sleep 2
	s_add_u32 s23, s23, 1
	s_cmp_lt_u32 s23, 0x4000
	s_cbranch_scc1 .Lxtail_wait_loop
.Lxtail_wait_ok:
	buffer_inv sc1
	s_waitcnt vmcnt(0)
.Lxtail_wait_done:
	s_or_b64 exec, exec, s[34:35]
	s_barrier
	v_readlane_b32 s22, v255, 30
	s_lshl_b32 s26, s22, 16
	s_lshl_b32 s20, s22, 9
	s_mulk_i32 s22, 0x300
	s_mov_b32 s23, s21
	s_lshl_b32 s55, s26, 1
	s_lshl_b64 s[26:27], s[20:21], 2
	s_lshl_b64 s[36:37], s[22:23], 2
	s_branch .LBB0_413

; __global__ void __launch_bounds__(NTHR, 2) fwd(Args args) {
	.amdhsa_kernel _Z3fwd4Args
		.amdhsa_group_segment_fixed_size 0
		.amdhsa_private_segment_fixed_size 0
		.amdhsa_kernarg_size 440
		.amdhsa_user_sgpr_count 2
		.amdhsa_user_sgpr_dispatch_ptr 0
		.amdhsa_user_sgpr_queue_ptr 0
		.amdhsa_user_sgpr_kernarg_segment_ptr 1
		.amdhsa_user_sgpr_dispatch_id 0
		.amdhsa_user_sgpr_kernarg_preload_length 0
		.amdhsa_user_sgpr_kernarg_preload_offset 0
		.amdhsa_user_sgpr_private_segment_size 0
		.amdhsa_uses_dynamic_stack 0
		.amdhsa_enable_private_segment 0
		.amdhsa_system_sgpr_workgroup_id_x 1
		.amdhsa_system_sgpr_workgroup_id_y 0
		.amdhsa_system_sgpr_workgroup_id_z 0
		.amdhsa_system_sgpr_workgroup_info 0
		.amdhsa_system_vgpr_workitem_id 2
		.amdhsa_next_free_vgpr 256
		.amdhsa_next_free_sgpr 100
		.amdhsa_accum_offset 256
		.amdhsa_reserve_vcc 1
		.amdhsa_float_round_mode_32 0
		.amdhsa_float_round_mode_16_64 0
		.amdhsa_float_denorm_mode_32 3
		.amdhsa_float_denorm_mode_16_64 3
		.amdhsa_dx10_clamp 1
		.amdhsa_ieee_mode 1
		.amdhsa_fp16_overflow 0
		.amdhsa_tg_split 0
		.amdhsa_exception_fp_ieee_invalid_op 0
		.amdhsa_exception_fp_denorm_src 0
		.amdhsa_exception_fp_ieee_div_zero 0
		.amdhsa_exception_fp_ieee_overflow 0
		.amdhsa_exception_fp_ieee_underflow 0
		.amdhsa_exception_fp_ieee_inexact 0
		.amdhsa_exception_int_div_zero 0
	.end_amdhsa_kernel

; __global__ void __launch_bounds__(NTHR, 2) fwd(Args args) {
amdhsa.kernels:
  - .agpr_count:     0
    .args:
      - .offset:         0
        .size:           184
        .value_kind:     by_value
      - .offset:         184
        .size:           4
        .value_kind:     hidden_block_count_x
      - .offset:         188
        .size:           4
        .value_kind:     hidden_block_count_y
      - .offset:         192
        .size:           4
        .value_kind:     hidden_block_count_z
      - .offset:         196
        .size:           2
        .value_kind:     hidden_group_size_x
      - .offset:         198
        .size:           2
        .value_kind:     hidden_group_size_y
      - .offset:         200
        .size:           2
        .value_kind:     hidden_group_size_z
      - .offset:         202
        .size:           2
        .value_kind:     hidden_remainder_x
      - .offset:         204
        .size:           2
        .value_kind:     hidden_remainder_y
      - .offset:         206
        .size:           2
        .value_kind:     hidden_remainder_z
      - .offset:         224
        .size:           8
        .value_kind:     hidden_global_offset_x
      - .offset:         232
        .size:           8
        .value_kind:     hidden_global_offset_y
      - .offset:         240
        .size:           8
        .value_kind:     hidden_global_offset_z
      - .offset:         248
        .size:           2
        .value_kind:     hidden_grid_dims
      - .offset:         272
        .size:           8
        .value_kind:     hidden_multigrid_sync_arg
      - .offset:         304
        .size:           4
        .value_kind:     hidden_dynamic_lds_size
    .group_segment_fixed_size: 0
    .kernarg_segment_align: 8
    .kernarg_segment_size: 440
    .language:       OpenCL C
    .language_version:
      - 2
      - 0
    .max_flat_workgroup_size: 512
    .name:           _Z3fwd4Args
    .private_segment_fixed_size: 0
    .sgpr_count:     106
    .sgpr_spill_count: 123
    .symbol:         _Z3fwd4Args.kd
    .uniform_work_group_size: 1
    .uses_dynamic_stack: false
    .vgpr_count:     256
    .vgpr_spill_count: 0
    .wavefront_size: 64
